# k-loop heads aligned to 64 B (.p2align 6) on top of static prio
# baseline (speedup 1.0000x reference)
; #define PG8_STAGE(bufoff, gbase, voff) do { _Pragma("unroll") for (int _i = 0; _i < 2; ++_i) \
;         __builtin_amdgcn_global_load_lds((const unsigned*)((const char*)(gbase) + (voff)[_i]), (PG8_LAS unsigned*)(lds + (bufoff) + ldsw + _i * 8192), 16, 0, 0); } while (0)
; #define PG8_LDA(dst, b, h) do { _Pragma("unroll") for (int m = 0; m < 4; ++m) _Pragma("unroll") for (int k = 0; k < 2; ++k) dst[m][k] = *(const PG8_LAS bf16x8*)(lds + PG8_SA(b, h) + aoff + m * 2048 + k * 1024); } while (0)
; #define PG8_LDB(dst, b, h) do { _Pragma("unroll") for (int n = 0; n < 2; ++n) _Pragma("unroll") for (int k = 0; k < 2; ++k) dst[n][k] = *(const PG8_LAS bf16x8*)(lds + PG8_SB(b, h) + boff + n * 2048 + k * 1024); } while (0)
; #define PG8_SCHED __builtin_amdgcn_sched_barrier(0)
; template <class Epi, class Sched, bool ALIGN_EPI = false, bool SP2 = false>
; __device__ __forceinline__ void gemm_phase(PG8_LAS unsigned char* lds, const Gemm g, const Sched& S, const Epi& E) {
;     ...
;         for (int t = 0; t < nt; t += 2) {
;             const bool last = (t == nt - 2);
;             const char* a1 = cA + (size_t)(t + 1) * kstep;
;             const char* a2 = last ? nA : cA + (size_t)(t + 2) * kstep; const char* b2 = last ? nB : cB + (size_t)(t + 2) * kstep;
;             const char* a3 = a2 + kstep; const char* b3 = b2 + kstep;
;             if (last && has_next) S.a_ready(nxt);
;             if constexpr (SP2) {
;             PG8_LDB(B0, 0, 0); PG8_LDB(B1, 0, 1); PG8_SCHED; PG8_LDA(At, 0, 0); PG8_STAGE(PG8_SA(1, 1), a1 + hstepA, voffA);
.Lsp_LBB0_365:
	.p2align 6
